# B1 epilogue hand-written: x_b stores write-through and the B1->S5 hand-off without an L2 write-back; silu(gate_b) stores paired into dwordx4
# speedup vs baseline: 1.0082x; 1.0082x over previous
; DI unsigned pk2(float lo, float hi) { const f32x2 v = {lo, hi}; const bf16x2_t b = __builtin_convertvector(v, bf16x2_t); return __builtin_bit_cast(unsigned, b); }
; DI float silu_f(float x) { return x * sigmoid_f(x); }
; DI f32x4 mfma16(bf16x8 a, bf16x8 b, f32x4 c) { return __builtin_amdgcn_mfma_f32_16x16x32_bf16(a, b, c, 0, 0, 0); }
;     ...
;     auto compute = [&](int cb, bool do_issue, int ikt, int ib) {
;         const char* base = lds + cb * BUF;
;         bf16x8 af[MT], bfr[NT];
; #pragma unroll
;         for (int nt = 0; nt < NT; ++nt) {
;             const int br = BM + (nt / NTS) * (BN / NSEG) + wc * (NTS * 16) + (nt % NTS) * 16;
;             bfr[nt] = *(const bf16x8*)(base + (br + l15) * 64 + rsw);
;         }
; #pragma unroll
;         for (int mt = 0; mt < MT; ++mt) af[mt] = *(const bf16x8*)(base + (wr * WM + mt * 16 + l15) * 64 + rsw);
;         constexpr int TOT = MT * NT, PER = (TOT + NIT - 1) / NIT;
; #pragma unroll
;         for (int part = 0; part < NIT; ++part) {
; #pragma unroll
;             for (int q = 0; q < PER; ++q) {
;                 const int idx = part * PER + q;
;                 if (idx < TOT) {
;                     const int mt = idx / NT, nt = idx % NT;
;                     acc[mt][nt] = SWAP ? mfma16(bfr[nt], af[mt], acc[mt][nt]) : mfma16(af[mt], bfr[nt], acc[mt][nt]);
;                 }
;             }
;             __builtin_amdgcn_sched_barrier(0);
;             if (do_issue) issue_one(ikt, ib, part);
;             __builtin_amdgcn_sched_barrier(0);
;         }
; DI void unit_B1(const Params& p, char* lds, int l, int chunk) {
;     ...
;     bf16_t* sgd = WS_PTR(bf16_t, OFF_SG) + (size_t)chunk * 128 * 256;
;     bf16_t* xbd = WS_PTR(bf16_t, OFF_XBB) + (size_t)(chunk >> 4) * 16 * 2048 * 16;
; #pragma unroll
;     for (int mt = 0; mt < 4; ++mt) {
;         const int tok = wr * 64 + mt * 16 + l15;
; #pragma unroll
;         for (int nt = 0; nt < 8; ++nt) {
;             f32x4 v = acc[mt][nt];
;             if (wc >= 2) {
;                 v[0] = silu_f(v[0]); v[1] = silu_f(v[1]); v[2] = silu_f(v[2]); v[3] = silu_f(v[3]);
;                 const int col = (wc & 1) * 128 + nt * 16 + quad * 4;
;                 *(u32x2*)(sgd + (size_t)tok * 256 + col) = (u32x2){pk2(v[0], v[1]), pk2(v[2], v[3])};
;             } else {
;                 const int g = (wc & 1) * 8 + nt, tb = (chunk & 15) * 128 + tok;
.Lpb1_join:
	s_waitcnt vmcnt(5)
	s_barrier
	v_add_u32_e32 v0, v136, v138
	v_add_u32_e32 v134, v136, v137
	ds_read_b128 v[130:133], v0 offset:8192
	ds_read_b128 v[136:139], v134
	ds_read_b128 v[140:143], v0 offset:9216
	ds_read_b128 v[144:147], v134 offset:1024
	ds_read_b128 v[148:151], v0 offset:10240
	ds_read_b128 v[152:155], v0 offset:11264
	ds_read_b128 v[156:159], v0 offset:12288
	ds_read_b128 v[160:163], v0 offset:13312
	ds_read_b128 v[164:167], v0 offset:14336
	ds_read_b128 v[168:171], v0 offset:15360
	ds_read_b128 v[172:175], v134 offset:2048
	ds_read_b128 v[176:179], v134 offset:3072
	s_waitcnt lgkmcnt(0)
	v_mfma_f32_16x16x32_bf16 v[126:129], v[130:133], v[136:139], v[126:129]
	v_bfe_u32 v180, v135, 6, 2
	v_mfma_f32_16x16x32_bf16 v[122:125], v[140:143], v[136:139], v[122:125]
	v_mfma_f32_16x16x32_bf16 v[118:121], v[148:151], v[136:139], v[118:121]
	v_mfma_f32_16x16x32_bf16 v[114:117], v[152:155], v[136:139], v[114:117]
	v_mfma_f32_16x16x32_bf16 v[110:113], v[156:159], v[136:139], v[110:113]
	v_mfma_f32_16x16x32_bf16 v[106:109], v[160:163], v[136:139], v[106:109]
	v_mfma_f32_16x16x32_bf16 v[102:105], v[164:167], v[136:139], v[102:105]
	v_mfma_f32_16x16x32_bf16 v[98:101], v[168:171], v[136:139], v[98:101]
	v_mfma_f32_16x16x32_bf16 v[94:97], v[130:133], v[144:147], v[94:97]
	v_mfma_f32_16x16x32_bf16 v[90:93], v[140:143], v[144:147], v[90:93]
	v_mfma_f32_16x16x32_bf16 v[86:89], v[148:151], v[144:147], v[86:89]
	v_mfma_f32_16x16x32_bf16 v[82:85], v[152:155], v[144:147], v[82:85]
	v_mfma_f32_16x16x32_bf16 v[78:81], v[156:159], v[144:147], v[78:81]
	v_mfma_f32_16x16x32_bf16 v[74:77], v[160:163], v[144:147], v[74:77]
	v_mfma_f32_16x16x32_bf16 v[70:73], v[164:167], v[144:147], v[70:73]
	v_mfma_f32_16x16x32_bf16 v[66:69], v[168:171], v[144:147], v[66:69]
	v_mfma_f32_16x16x32_bf16 v[62:65], v[130:133], v[172:175], v[62:65]
	v_mfma_f32_16x16x32_bf16 v[58:61], v[140:143], v[172:175], v[58:61]
	v_mfma_f32_16x16x32_bf16 v[54:57], v[148:151], v[172:175], v[54:57]
	v_mfma_f32_16x16x32_bf16 v[50:53], v[152:155], v[172:175], v[50:53]
	v_mfma_f32_16x16x32_bf16 v[46:49], v[156:159], v[172:175], v[46:49]
	v_mfma_f32_16x16x32_bf16 v[42:45], v[160:163], v[172:175], v[42:45]
	v_mfma_f32_16x16x32_bf16 v[38:41], v[164:167], v[172:175], v[38:41]
	v_mfma_f32_16x16x32_bf16 v[34:37], v[168:171], v[172:175], v[34:37]
	v_mfma_f32_16x16x32_bf16 v[30:33], v[130:133], v[176:179], v[30:33]
	v_mfma_f32_16x16x32_bf16 v[26:29], v[140:143], v[176:179], v[26:29]
	v_mfma_f32_16x16x32_bf16 v[22:25], v[148:151], v[176:179], v[22:25]
	v_mfma_f32_16x16x32_bf16 v[18:21], v[152:155], v[176:179], v[18:21]
	v_mfma_f32_16x16x32_bf16 v[14:17], v[156:159], v[176:179], v[14:17]
	v_mfma_f32_16x16x32_bf16 v[10:13], v[160:163], v[176:179], v[10:13]
	v_mfma_f32_16x16x32_bf16 v[6:9], v[164:167], v[176:179], v[6:9]
	v_mfma_f32_16x16x32_bf16 v[2:5], v[168:171], v[176:179], v[2:5]
	s_waitcnt vmcnt(0)
	s_barrier
	ds_read_b128 v[130:133], v0 offset:49152
	ds_read_b128 v[136:139], v134 offset:40960
	ds_read_b128 v[140:143], v0 offset:50176
	ds_read_b128 v[144:147], v134 offset:41984
	ds_read_b128 v[148:151], v0 offset:51200
	ds_read_b128 v[152:155], v0 offset:52224
	ds_read_b128 v[156:159], v0 offset:53248
	ds_read_b128 v[160:163], v0 offset:54272
	ds_read_b128 v[164:167], v0 offset:55296
	ds_read_b128 v[168:171], v0 offset:56320
	ds_read_b128 v[172:175], v134 offset:43008
	ds_read_b128 v[176:179], v134 offset:44032
	s_waitcnt lgkmcnt(0)
	v_mfma_f32_16x16x32_bf16 v[126:129], v[130:133], v[136:139], v[126:129]
	v_and_b32_e32 v181, 15, v135
	v_mfma_f32_16x16x32_bf16 v[122:125], v[140:143], v[136:139], v[122:125]
	v_mfma_f32_16x16x32_bf16 v[118:121], v[148:151], v[136:139], v[118:121]
	v_mfma_f32_16x16x32_bf16 v[114:117], v[152:155], v[136:139], v[114:117]
	v_mfma_f32_16x16x32_bf16 v[110:113], v[156:159], v[136:139], v[110:113]
	v_mfma_f32_16x16x32_bf16 v[106:109], v[160:163], v[136:139], v[106:109]
	v_mfma_f32_16x16x32_bf16 v[102:105], v[164:167], v[136:139], v[102:105]
	v_mfma_f32_16x16x32_bf16 v[98:101], v[168:171], v[136:139], v[98:101]
	v_mfma_f32_16x16x32_bf16 v[94:97], v[130:133], v[144:147], v[94:97]
	v_mfma_f32_16x16x32_bf16 v[90:93], v[140:143], v[144:147], v[90:93]
	v_mfma_f32_16x16x32_bf16 v[86:89], v[148:151], v[144:147], v[86:89]
	v_mfma_f32_16x16x32_bf16 v[82:85], v[152:155], v[144:147], v[82:85]
	v_mfma_f32_16x16x32_bf16 v[78:81], v[156:159], v[144:147], v[78:81]
	v_mfma_f32_16x16x32_bf16 v[74:77], v[160:163], v[144:147], v[74:77]
	v_mfma_f32_16x16x32_bf16 v[70:73], v[164:167], v[144:147], v[70:73]
	v_mfma_f32_16x16x32_bf16 v[66:69], v[168:171], v[144:147], v[66:69]
	v_mfma_f32_16x16x32_bf16 v[62:65], v[130:133], v[172:175], v[62:65]
	v_mfma_f32_16x16x32_bf16 v[58:61], v[140:143], v[172:175], v[58:61]
	v_mfma_f32_16x16x32_bf16 v[54:57], v[148:151], v[172:175], v[54:57]
	v_mfma_f32_16x16x32_bf16 v[50:53], v[152:155], v[172:175], v[50:53]
	v_mfma_f32_16x16x32_bf16 v[46:49], v[156:159], v[172:175], v[46:49]
	v_mfma_f32_16x16x32_bf16 v[42:45], v[160:163], v[172:175], v[42:45]
	v_mfma_f32_16x16x32_bf16 v[38:41], v[164:167], v[172:175], v[38:41]
	v_mfma_f32_16x16x32_bf16 v[34:37], v[168:171], v[172:175], v[34:37]
	v_mfma_f32_16x16x32_bf16 v[30:33], v[130:133], v[176:179], v[30:33]
	v_mfma_f32_16x16x32_bf16 v[26:29], v[140:143], v[176:179], v[26:29]
	v_mfma_f32_16x16x32_bf16 v[22:25], v[148:151], v[176:179], v[22:25]
	v_mfma_f32_16x16x32_bf16 v[18:21], v[152:155], v[176:179], v[18:21]
	v_mfma_f32_16x16x32_bf16 v[14:17], v[156:159], v[176:179], v[14:17]
	v_mfma_f32_16x16x32_bf16 v[10:13], v[160:163], v[176:179], v[10:13]
	v_mfma_f32_16x16x32_bf16 v[6:9], v[164:167], v[176:179], v[6:9]
	v_mfma_f32_16x16x32_bf16 v[2:5], v[168:171], v[176:179], v[2:5]
	v_and_b32_e32 v130, 15, v212
	v_bfe_u32 v131, v212, 4, 2
	v_lshrrev_b32_e32 v132, 6, v212
	v_readlane_b32 s92, v244, 48
	v_readlane_b32 s93, v244, 49
	v_readlane_b32 s94, v243, 0
	v_readlane_b32 s95, v243, 1
	v_readfirstlane_b32 s90, v132
	s_nop 3
	s_lshl_b32 s0, s2, 16
	s_add_u32 s92, s92, s0
	s_addc_u32 s93, s93, 0
	s_ashr_i32 s0, s2, 4
	s_lshl_b32 s0, s0, 20
	s_add_u32 s94, s94, s0
	s_addc_u32 s95, s95, 0
	s_lshr_b32 s91, s90, 2
	s_and_b32 s1, s90, 1
	s_bitcmp1_b32 s90, 1
	s_cbranch_scc1 .Lb1e_sg
; DI unsigned pk2(float lo, float hi) { const f32x2 v = {lo, hi}; const bf16x2_t b = __builtin_convertvector(v, bf16x2_t); return __builtin_bit_cast(unsigned, b); }
; DI float silu_f(float x) { return x * sigmoid_f(x); }
; DI void unit_B1(const Params& p, char* lds, int l, int chunk) {
;     ...
; #pragma unroll
;     for (int mt = 0; mt < 4; ++mt) {
;         const int tok = wr * 64 + mt * 16 + l15;
; #pragma unroll
;         for (int nt = 0; nt < 8; ++nt) {
;             f32x4 v = acc[mt][nt];
;             if (wc >= 2) {
;                 v[0] = silu_f(v[0]); v[1] = silu_f(v[1]); v[2] = silu_f(v[2]); v[3] = silu_f(v[3]);
;                 const int col = (wc & 1) * 128 + nt * 16 + quad * 4;
;                 *(u32x2*)(sgd + (size_t)tok * 256 + col) = (u32x2){pk2(v[0], v[1]), pk2(v[2], v[3])};
;             } else {
;                 const int g = (wc & 1) * 8 + nt, tb = (chunk & 15) * 128 + tok;
;                 *(u32x2*)(xbd + ((size_t)g * 2048 + tb) * 16 + quad * 4) = (u32x2){pk2(v[0], v[1]), pk2(v[2], v[3])};
;             }
;         }
;     }
	s_lshl_b32 s0, s1, 19
	s_and_b32 s3, s2, 15
	s_lshl_b32 s3, s3, 12
	s_add_u32 s0, s0, s3
	s_lshl_b32 s3, s91, 11
	s_add_u32 s0, s0, s3
	s_add_u32 s94, s94, s0
	s_addc_u32 s95, s95, 0
	v_lshlrev_b32_e32 v133, 5, v130
	v_lshl_add_u32 v133, v131, 3, v133
	v_cvt_pk_bf16_f32 v134, v126, v127
	v_cvt_pk_bf16_f32 v135, v128, v129
	global_store_dwordx2 v133, v[134:135], s[94:95] sc1
	v_cvt_pk_bf16_f32 v136, v94, v95
	v_cvt_pk_bf16_f32 v137, v96, v97
	global_store_dwordx2 v133, v[136:137], s[94:95] offset:512 sc1
	v_cvt_pk_bf16_f32 v138, v62, v63
	v_cvt_pk_bf16_f32 v139, v64, v65
	global_store_dwordx2 v133, v[138:139], s[94:95] offset:1024 sc1
	v_cvt_pk_bf16_f32 v140, v30, v31
	v_cvt_pk_bf16_f32 v141, v32, v33
	global_store_dwordx2 v133, v[140:141], s[94:95] offset:1536 sc1
	s_add_u32 s94, s94, 0x10000
	s_addc_u32 s95, s95, 0
	v_cvt_pk_bf16_f32 v142, v122, v123
	v_cvt_pk_bf16_f32 v143, v124, v125
	global_store_dwordx2 v133, v[142:143], s[94:95] sc1
	v_cvt_pk_bf16_f32 v144, v90, v91
	v_cvt_pk_bf16_f32 v145, v92, v93
	global_store_dwordx2 v133, v[144:145], s[94:95] offset:512 sc1
	v_cvt_pk_bf16_f32 v146, v58, v59
	v_cvt_pk_bf16_f32 v147, v60, v61
	global_store_dwordx2 v133, v[146:147], s[94:95] offset:1024 sc1
	v_cvt_pk_bf16_f32 v148, v26, v27
	v_cvt_pk_bf16_f32 v149, v28, v29
	global_store_dwordx2 v133, v[148:149], s[94:95] offset:1536 sc1
	s_add_u32 s94, s94, 0x10000
	s_addc_u32 s95, s95, 0
	v_cvt_pk_bf16_f32 v134, v118, v119
	v_cvt_pk_bf16_f32 v135, v120, v121
	global_store_dwordx2 v133, v[134:135], s[94:95] sc1
	v_cvt_pk_bf16_f32 v136, v86, v87
	v_cvt_pk_bf16_f32 v137, v88, v89
	global_store_dwordx2 v133, v[136:137], s[94:95] offset:512 sc1
	v_cvt_pk_bf16_f32 v138, v54, v55
	v_cvt_pk_bf16_f32 v139, v56, v57
	global_store_dwordx2 v133, v[138:139], s[94:95] offset:1024 sc1
	v_cvt_pk_bf16_f32 v140, v22, v23
	v_cvt_pk_bf16_f32 v141, v24, v25
	global_store_dwordx2 v133, v[140:141], s[94:95] offset:1536 sc1
	s_add_u32 s94, s94, 0x10000
	s_addc_u32 s95, s95, 0
	v_cvt_pk_bf16_f32 v142, v114, v115
	v_cvt_pk_bf16_f32 v143, v116, v117
	global_store_dwordx2 v133, v[142:143], s[94:95] sc1
	v_cvt_pk_bf16_f32 v144, v82, v83
	v_cvt_pk_bf16_f32 v145, v84, v85
	global_store_dwordx2 v133, v[144:145], s[94:95] offset:512 sc1
	v_cvt_pk_bf16_f32 v146, v50, v51
	v_cvt_pk_bf16_f32 v147, v52, v53
	global_store_dwordx2 v133, v[146:147], s[94:95] offset:1024 sc1
	v_cvt_pk_bf16_f32 v148, v18, v19
	v_cvt_pk_bf16_f32 v149, v20, v21
	global_store_dwordx2 v133, v[148:149], s[94:95] offset:1536 sc1
	s_add_u32 s94, s94, 0x10000
	s_addc_u32 s95, s95, 0
	v_cvt_pk_bf16_f32 v134, v110, v111
	v_cvt_pk_bf16_f32 v135, v112, v113
	global_store_dwordx2 v133, v[134:135], s[94:95] sc1
	v_cvt_pk_bf16_f32 v136, v78, v79
	v_cvt_pk_bf16_f32 v137, v80, v81
	global_store_dwordx2 v133, v[136:137], s[94:95] offset:512 sc1
	v_cvt_pk_bf16_f32 v138, v46, v47
	v_cvt_pk_bf16_f32 v139, v48, v49
	global_store_dwordx2 v133, v[138:139], s[94:95] offset:1024 sc1
	v_cvt_pk_bf16_f32 v140, v14, v15
	v_cvt_pk_bf16_f32 v141, v16, v17
	global_store_dwordx2 v133, v[140:141], s[94:95] offset:1536 sc1
	s_add_u32 s94, s94, 0x10000
	s_addc_u32 s95, s95, 0
	v_cvt_pk_bf16_f32 v142, v106, v107
	v_cvt_pk_bf16_f32 v143, v108, v109
	global_store_dwordx2 v133, v[142:143], s[94:95] sc1
	v_cvt_pk_bf16_f32 v144, v74, v75
	v_cvt_pk_bf16_f32 v145, v76, v77
	global_store_dwordx2 v133, v[144:145], s[94:95] offset:512 sc1
	v_cvt_pk_bf16_f32 v146, v42, v43
	v_cvt_pk_bf16_f32 v147, v44, v45
	global_store_dwordx2 v133, v[146:147], s[94:95] offset:1024 sc1
	v_cvt_pk_bf16_f32 v148, v10, v11
	v_cvt_pk_bf16_f32 v149, v12, v13
	global_store_dwordx2 v133, v[148:149], s[94:95] offset:1536 sc1
	s_add_u32 s94, s94, 0x10000
	s_addc_u32 s95, s95, 0
	v_cvt_pk_bf16_f32 v134, v102, v103
	v_cvt_pk_bf16_f32 v135, v104, v105
	global_store_dwordx2 v133, v[134:135], s[94:95] sc1
	v_cvt_pk_bf16_f32 v136, v70, v71
	v_cvt_pk_bf16_f32 v137, v72, v73
	global_store_dwordx2 v133, v[136:137], s[94:95] offset:512 sc1
	v_cvt_pk_bf16_f32 v138, v38, v39
	v_cvt_pk_bf16_f32 v139, v40, v41
	global_store_dwordx2 v133, v[138:139], s[94:95] offset:1024 sc1
	v_cvt_pk_bf16_f32 v140, v6, v7
	v_cvt_pk_bf16_f32 v141, v8, v9
	global_store_dwordx2 v133, v[140:141], s[94:95] offset:1536 sc1
	s_add_u32 s94, s94, 0x10000
	s_addc_u32 s95, s95, 0
	v_cvt_pk_bf16_f32 v142, v98, v99
	v_cvt_pk_bf16_f32 v143, v100, v101
	global_store_dwordx2 v133, v[142:143], s[94:95] sc1
	v_cvt_pk_bf16_f32 v144, v66, v67
	v_cvt_pk_bf16_f32 v145, v68, v69
	global_store_dwordx2 v133, v[144:145], s[94:95] offset:512 sc1
	v_cvt_pk_bf16_f32 v146, v34, v35
	v_cvt_pk_bf16_f32 v147, v36, v37
	global_store_dwordx2 v133, v[146:147], s[94:95] offset:1024 sc1
	v_cvt_pk_bf16_f32 v148, v2, v3
	v_cvt_pk_bf16_f32 v149, v4, v5
	global_store_dwordx2 v133, v[148:149], s[94:95] offset:1536 sc1
	s_branch .Lb1e_done
; DI unsigned pk2(float lo, float hi) { const f32x2 v = {lo, hi}; const bf16x2_t b = __builtin_convertvector(v, bf16x2_t); return __builtin_bit_cast(unsigned, b); }
; DI float sigmoid_f(float x) { return __builtin_amdgcn_rcpf(1.f + __builtin_amdgcn_exp2f(x * -1.44269504089f)); }
; DI float silu_f(float x) { return x * sigmoid_f(x); }
; DI void unit_B1(const Params& p, char* lds, int l, int chunk) {
;     ...
; #pragma unroll
;     for (int mt = 0; mt < 4; ++mt) {
;         const int tok = wr * 64 + mt * 16 + l15;
; #pragma unroll
;         for (int nt = 0; nt < 8; ++nt) {
;             f32x4 v = acc[mt][nt];
;             if (wc >= 2) {
;                 v[0] = silu_f(v[0]); v[1] = silu_f(v[1]); v[2] = silu_f(v[2]); v[3] = silu_f(v[3]);
;                 const int col = (wc & 1) * 128 + nt * 16 + quad * 4;
;                 *(u32x2*)(sgd + (size_t)tok * 256 + col) = (u32x2){pk2(v[0], v[1]), pk2(v[2], v[3])};
.Lb1e_sg:
	s_lshl_b32 s0, s1, 8
	s_lshl_b32 s3, s91, 15
	s_add_u32 s0, s0, s3
	s_add_u32 s92, s92, s0
	s_addc_u32 s93, s93, 0
	v_and_b32_e32 v133, 1, v131
	v_lshlrev_b32_e32 v133, 5, v133
	v_lshrrev_b32_e32 v134, 1, v131
	v_lshl_or_b32 v133, v134, 4, v133
	v_lshl_or_b32 v133, v130, 9, v133
	v_mul_f32_e32 v152, 0xbfb8aa3b, v126
	v_mul_f32_e32 v153, 0xbfb8aa3b, v127
	v_mul_f32_e32 v154, 0xbfb8aa3b, v128
	v_mul_f32_e32 v155, 0xbfb8aa3b, v129
	v_exp_f32_e32 v152, v152
	v_exp_f32_e32 v153, v153
	v_exp_f32_e32 v154, v154
	v_exp_f32_e32 v155, v155
	v_add_f32_e32 v152, 1.0, v152
	v_add_f32_e32 v153, 1.0, v153
	v_add_f32_e32 v154, 1.0, v154
	v_add_f32_e32 v155, 1.0, v155
	v_rcp_f32_e32 v152, v152
	v_rcp_f32_e32 v153, v153
	v_rcp_f32_e32 v154, v154
	v_rcp_f32_e32 v155, v155
	v_mul_f32_e32 v152, v126, v152
	v_mul_f32_e32 v153, v127, v153
	v_mul_f32_e32 v154, v128, v154
	v_mul_f32_e32 v155, v129, v155
	v_cvt_pk_bf16_f32 v136, v152, v153
	v_cvt_pk_bf16_f32 v137, v154, v155
	v_mul_f32_e32 v156, 0xbfb8aa3b, v122
	v_mul_f32_e32 v157, 0xbfb8aa3b, v123
	v_mul_f32_e32 v158, 0xbfb8aa3b, v124
	v_mul_f32_e32 v159, 0xbfb8aa3b, v125
	v_exp_f32_e32 v156, v156
	v_exp_f32_e32 v157, v157
	v_exp_f32_e32 v158, v158
	v_exp_f32_e32 v159, v159
	v_add_f32_e32 v156, 1.0, v156
	v_add_f32_e32 v157, 1.0, v157
	v_add_f32_e32 v158, 1.0, v158
	v_add_f32_e32 v159, 1.0, v159
	v_rcp_f32_e32 v156, v156
	v_rcp_f32_e32 v157, v157
	v_rcp_f32_e32 v158, v158
	v_rcp_f32_e32 v159, v159
	v_mul_f32_e32 v156, v122, v156
	v_mul_f32_e32 v157, v123, v157
	v_mul_f32_e32 v158, v124, v158
	v_mul_f32_e32 v159, v125, v159
	v_cvt_pk_bf16_f32 v138, v156, v157
	v_cvt_pk_bf16_f32 v139, v158, v159
	s_nop 1
	v_permlane16_swap_b32 v136, v138
	v_permlane16_swap_b32 v137, v139
	global_store_dwordx4 v133, v[136:139], s[92:93]
	v_mul_f32_e32 v152, 0xbfb8aa3b, v118
	v_mul_f32_e32 v153, 0xbfb8aa3b, v119
	v_mul_f32_e32 v154, 0xbfb8aa3b, v120
	v_mul_f32_e32 v155, 0xbfb8aa3b, v121
	v_exp_f32_e32 v152, v152
	v_exp_f32_e32 v153, v153
	v_exp_f32_e32 v154, v154
	v_exp_f32_e32 v155, v155
	v_add_f32_e32 v152, 1.0, v152
	v_add_f32_e32 v153, 1.0, v153
	v_add_f32_e32 v154, 1.0, v154
	v_add_f32_e32 v155, 1.0, v155
	v_rcp_f32_e32 v152, v152
	v_rcp_f32_e32 v153, v153
	v_rcp_f32_e32 v154, v154
	v_rcp_f32_e32 v155, v155
	v_mul_f32_e32 v152, v118, v152
	v_mul_f32_e32 v153, v119, v153
	v_mul_f32_e32 v154, v120, v154
	v_mul_f32_e32 v155, v121, v155
	v_cvt_pk_bf16_f32 v140, v152, v153
	v_cvt_pk_bf16_f32 v141, v154, v155
	v_mul_f32_e32 v156, 0xbfb8aa3b, v114
	v_mul_f32_e32 v157, 0xbfb8aa3b, v115
	v_mul_f32_e32 v158, 0xbfb8aa3b, v116
	v_mul_f32_e32 v159, 0xbfb8aa3b, v117
	v_exp_f32_e32 v156, v156
	v_exp_f32_e32 v157, v157
	v_exp_f32_e32 v158, v158
	v_exp_f32_e32 v159, v159
	v_add_f32_e32 v156, 1.0, v156
	v_add_f32_e32 v157, 1.0, v157
	v_add_f32_e32 v158, 1.0, v158
	v_add_f32_e32 v159, 1.0, v159
	v_rcp_f32_e32 v156, v156
	v_rcp_f32_e32 v157, v157
	v_rcp_f32_e32 v158, v158
	v_rcp_f32_e32 v159, v159
	v_mul_f32_e32 v156, v114, v156
	v_mul_f32_e32 v157, v115, v157
	v_mul_f32_e32 v158, v116, v158
	v_mul_f32_e32 v159, v117, v159
	v_cvt_pk_bf16_f32 v142, v156, v157
	v_cvt_pk_bf16_f32 v143, v158, v159
	s_nop 1
	v_permlane16_swap_b32 v140, v142
	v_permlane16_swap_b32 v141, v143
	global_store_dwordx4 v133, v[140:143], s[92:93] offset:64
	v_mul_f32_e32 v152, 0xbfb8aa3b, v110
	v_mul_f32_e32 v153, 0xbfb8aa3b, v111
	v_mul_f32_e32 v154, 0xbfb8aa3b, v112
	v_mul_f32_e32 v155, 0xbfb8aa3b, v113
	v_exp_f32_e32 v152, v152
	v_exp_f32_e32 v153, v153
	v_exp_f32_e32 v154, v154
	v_exp_f32_e32 v155, v155
	v_add_f32_e32 v152, 1.0, v152
	v_add_f32_e32 v153, 1.0, v153
	v_add_f32_e32 v154, 1.0, v154
	v_add_f32_e32 v155, 1.0, v155
	v_rcp_f32_e32 v152, v152
	v_rcp_f32_e32 v153, v153
	v_rcp_f32_e32 v154, v154
	v_rcp_f32_e32 v155, v155
	v_mul_f32_e32 v152, v110, v152
	v_mul_f32_e32 v153, v111, v153
	v_mul_f32_e32 v154, v112, v154
	v_mul_f32_e32 v155, v113, v155
	v_cvt_pk_bf16_f32 v144, v152, v153
	v_cvt_pk_bf16_f32 v145, v154, v155
	v_mul_f32_e32 v156, 0xbfb8aa3b, v106
	v_mul_f32_e32 v157, 0xbfb8aa3b, v107
	v_mul_f32_e32 v158, 0xbfb8aa3b, v108
	v_mul_f32_e32 v159, 0xbfb8aa3b, v109
	v_exp_f32_e32 v156, v156
	v_exp_f32_e32 v157, v157
	v_exp_f32_e32 v158, v158
	v_exp_f32_e32 v159, v159
	v_add_f32_e32 v156, 1.0, v156
	v_add_f32_e32 v157, 1.0, v157
	v_add_f32_e32 v158, 1.0, v158
	v_add_f32_e32 v159, 1.0, v159
	v_rcp_f32_e32 v156, v156
	v_rcp_f32_e32 v157, v157
	v_rcp_f32_e32 v158, v158
	v_rcp_f32_e32 v159, v159
	v_mul_f32_e32 v156, v106, v156
	v_mul_f32_e32 v157, v107, v157
	v_mul_f32_e32 v158, v108, v158
	v_mul_f32_e32 v159, v109, v159
	v_cvt_pk_bf16_f32 v146, v156, v157
	v_cvt_pk_bf16_f32 v147, v158, v159
	s_nop 1
	v_permlane16_swap_b32 v144, v146
	v_permlane16_swap_b32 v145, v147
	global_store_dwordx4 v133, v[144:147], s[92:93] offset:128
	v_mul_f32_e32 v152, 0xbfb8aa3b, v102
	v_mul_f32_e32 v153, 0xbfb8aa3b, v103
	v_mul_f32_e32 v154, 0xbfb8aa3b, v104
	v_mul_f32_e32 v155, 0xbfb8aa3b, v105
	v_exp_f32_e32 v152, v152
	v_exp_f32_e32 v153, v153
	v_exp_f32_e32 v154, v154
	v_exp_f32_e32 v155, v155
	v_add_f32_e32 v152, 1.0, v152
	v_add_f32_e32 v153, 1.0, v153
	v_add_f32_e32 v154, 1.0, v154
	v_add_f32_e32 v155, 1.0, v155
	v_rcp_f32_e32 v152, v152
	v_rcp_f32_e32 v153, v153
	v_rcp_f32_e32 v154, v154
	v_rcp_f32_e32 v155, v155
	v_mul_f32_e32 v152, v102, v152
	v_mul_f32_e32 v153, v103, v153
	v_mul_f32_e32 v154, v104, v154
	v_mul_f32_e32 v155, v105, v155
	v_cvt_pk_bf16_f32 v148, v152, v153
	v_cvt_pk_bf16_f32 v149, v154, v155
	v_mul_f32_e32 v156, 0xbfb8aa3b, v98
	v_mul_f32_e32 v157, 0xbfb8aa3b, v99
	v_mul_f32_e32 v158, 0xbfb8aa3b, v100
	v_mul_f32_e32 v159, 0xbfb8aa3b, v101
; DI unsigned pk2(float lo, float hi) { const f32x2 v = {lo, hi}; const bf16x2_t b = __builtin_convertvector(v, bf16x2_t); return __builtin_bit_cast(unsigned, b); }
; DI float sigmoid_f(float x) { return __builtin_amdgcn_rcpf(1.f + __builtin_amdgcn_exp2f(x * -1.44269504089f)); }
; DI float silu_f(float x) { return x * sigmoid_f(x); }
; DI void unit_B1(const Params& p, char* lds, int l, int chunk) {
;     ...
;         for (int nt = 0; nt < 8; ++nt) {
;             f32x4 v = acc[mt][nt];
;             if (wc >= 2) {
;                 v[0] = silu_f(v[0]); v[1] = silu_f(v[1]); v[2] = silu_f(v[2]); v[3] = silu_f(v[3]);
;                 const int col = (wc & 1) * 128 + nt * 16 + quad * 4;
;                 *(u32x2*)(sgd + (size_t)tok * 256 + col) = (u32x2){pk2(v[0], v[1]), pk2(v[2], v[3])};
	v_exp_f32_e32 v156, v156
	v_exp_f32_e32 v157, v157
	v_exp_f32_e32 v158, v158
	v_exp_f32_e32 v159, v159
	v_add_f32_e32 v156, 1.0, v156
	v_add_f32_e32 v157, 1.0, v157
	v_add_f32_e32 v158, 1.0, v158
	v_add_f32_e32 v159, 1.0, v159
	v_rcp_f32_e32 v156, v156
	v_rcp_f32_e32 v157, v157
	v_rcp_f32_e32 v158, v158
	v_rcp_f32_e32 v159, v159
	v_mul_f32_e32 v156, v98, v156
	v_mul_f32_e32 v157, v99, v157
	v_mul_f32_e32 v158, v100, v158
	v_mul_f32_e32 v159, v101, v159
	v_cvt_pk_bf16_f32 v150, v156, v157
	v_cvt_pk_bf16_f32 v151, v158, v159
	s_nop 1
	v_permlane16_swap_b32 v148, v150
	v_permlane16_swap_b32 v149, v151
	global_store_dwordx4 v133, v[148:151], s[92:93] offset:192
	s_add_u32 s92, s92, 0x2000
	s_addc_u32 s93, s93, 0
	v_mul_f32_e32 v152, 0xbfb8aa3b, v94
	v_mul_f32_e32 v153, 0xbfb8aa3b, v95
	v_mul_f32_e32 v154, 0xbfb8aa3b, v96
	v_mul_f32_e32 v155, 0xbfb8aa3b, v97
	v_exp_f32_e32 v152, v152
	v_exp_f32_e32 v153, v153
	v_exp_f32_e32 v154, v154
	v_exp_f32_e32 v155, v155
	v_add_f32_e32 v152, 1.0, v152
	v_add_f32_e32 v153, 1.0, v153
	v_add_f32_e32 v154, 1.0, v154
	v_add_f32_e32 v155, 1.0, v155
	v_rcp_f32_e32 v152, v152
	v_rcp_f32_e32 v153, v153
	v_rcp_f32_e32 v154, v154
	v_rcp_f32_e32 v155, v155
	v_mul_f32_e32 v152, v94, v152
	v_mul_f32_e32 v153, v95, v153
	v_mul_f32_e32 v154, v96, v154
	v_mul_f32_e32 v155, v97, v155
	v_cvt_pk_bf16_f32 v136, v152, v153
	v_cvt_pk_bf16_f32 v137, v154, v155
	v_mul_f32_e32 v156, 0xbfb8aa3b, v90
	v_mul_f32_e32 v157, 0xbfb8aa3b, v91
	v_mul_f32_e32 v158, 0xbfb8aa3b, v92
	v_mul_f32_e32 v159, 0xbfb8aa3b, v93
	v_exp_f32_e32 v156, v156
	v_exp_f32_e32 v157, v157
	v_exp_f32_e32 v158, v158
	v_exp_f32_e32 v159, v159
	v_add_f32_e32 v156, 1.0, v156
	v_add_f32_e32 v157, 1.0, v157
	v_add_f32_e32 v158, 1.0, v158
	v_add_f32_e32 v159, 1.0, v159
	v_rcp_f32_e32 v156, v156
	v_rcp_f32_e32 v157, v157
	v_rcp_f32_e32 v158, v158
	v_rcp_f32_e32 v159, v159
	v_mul_f32_e32 v156, v90, v156
	v_mul_f32_e32 v157, v91, v157
	v_mul_f32_e32 v158, v92, v158
	v_mul_f32_e32 v159, v93, v159
	v_cvt_pk_bf16_f32 v138, v156, v157
	v_cvt_pk_bf16_f32 v139, v158, v159
	s_nop 1
	v_permlane16_swap_b32 v136, v138
	v_permlane16_swap_b32 v137, v139
	global_store_dwordx4 v133, v[136:139], s[92:93]
	v_mul_f32_e32 v152, 0xbfb8aa3b, v86
	v_mul_f32_e32 v153, 0xbfb8aa3b, v87
	v_mul_f32_e32 v154, 0xbfb8aa3b, v88
	v_mul_f32_e32 v155, 0xbfb8aa3b, v89
	v_exp_f32_e32 v152, v152
	v_exp_f32_e32 v153, v153
	v_exp_f32_e32 v154, v154
	v_exp_f32_e32 v155, v155
	v_add_f32_e32 v152, 1.0, v152
	v_add_f32_e32 v153, 1.0, v153
	v_add_f32_e32 v154, 1.0, v154
	v_add_f32_e32 v155, 1.0, v155
	v_rcp_f32_e32 v152, v152
	v_rcp_f32_e32 v153, v153
	v_rcp_f32_e32 v154, v154
	v_rcp_f32_e32 v155, v155
	v_mul_f32_e32 v152, v86, v152
	v_mul_f32_e32 v153, v87, v153
	v_mul_f32_e32 v154, v88, v154
	v_mul_f32_e32 v155, v89, v155
	v_cvt_pk_bf16_f32 v140, v152, v153
	v_cvt_pk_bf16_f32 v141, v154, v155
	v_mul_f32_e32 v156, 0xbfb8aa3b, v82
	v_mul_f32_e32 v157, 0xbfb8aa3b, v83
	v_mul_f32_e32 v158, 0xbfb8aa3b, v84
	v_mul_f32_e32 v159, 0xbfb8aa3b, v85
	v_exp_f32_e32 v156, v156
	v_exp_f32_e32 v157, v157
	v_exp_f32_e32 v158, v158
	v_exp_f32_e32 v159, v159
	v_add_f32_e32 v156, 1.0, v156
	v_add_f32_e32 v157, 1.0, v157
	v_add_f32_e32 v158, 1.0, v158
	v_add_f32_e32 v159, 1.0, v159
	v_rcp_f32_e32 v156, v156
	v_rcp_f32_e32 v157, v157
	v_rcp_f32_e32 v158, v158
	v_rcp_f32_e32 v159, v159
	v_mul_f32_e32 v156, v82, v156
	v_mul_f32_e32 v157, v83, v157
	v_mul_f32_e32 v158, v84, v158
	v_mul_f32_e32 v159, v85, v159
	v_cvt_pk_bf16_f32 v142, v156, v157
	v_cvt_pk_bf16_f32 v143, v158, v159
	s_nop 1
	v_permlane16_swap_b32 v140, v142
	v_permlane16_swap_b32 v141, v143
	global_store_dwordx4 v133, v[140:143], s[92:93] offset:64
	v_mul_f32_e32 v152, 0xbfb8aa3b, v78
	v_mul_f32_e32 v153, 0xbfb8aa3b, v79
	v_mul_f32_e32 v154, 0xbfb8aa3b, v80
	v_mul_f32_e32 v155, 0xbfb8aa3b, v81
	v_exp_f32_e32 v152, v152
	v_exp_f32_e32 v153, v153
	v_exp_f32_e32 v154, v154
	v_exp_f32_e32 v155, v155
	v_add_f32_e32 v152, 1.0, v152
	v_add_f32_e32 v153, 1.0, v153
	v_add_f32_e32 v154, 1.0, v154
	v_add_f32_e32 v155, 1.0, v155
	v_rcp_f32_e32 v152, v152
	v_rcp_f32_e32 v153, v153
	v_rcp_f32_e32 v154, v154
	v_rcp_f32_e32 v155, v155
	v_mul_f32_e32 v152, v78, v152
	v_mul_f32_e32 v153, v79, v153
	v_mul_f32_e32 v154, v80, v154
	v_mul_f32_e32 v155, v81, v155
	v_cvt_pk_bf16_f32 v144, v152, v153
	v_cvt_pk_bf16_f32 v145, v154, v155
	v_mul_f32_e32 v156, 0xbfb8aa3b, v74
	v_mul_f32_e32 v157, 0xbfb8aa3b, v75
	v_mul_f32_e32 v158, 0xbfb8aa3b, v76
	v_mul_f32_e32 v159, 0xbfb8aa3b, v77
	v_exp_f32_e32 v156, v156
	v_exp_f32_e32 v157, v157
	v_exp_f32_e32 v158, v158
	v_exp_f32_e32 v159, v159
	v_add_f32_e32 v156, 1.0, v156
	v_add_f32_e32 v157, 1.0, v157
	v_add_f32_e32 v158, 1.0, v158
	v_add_f32_e32 v159, 1.0, v159
	v_rcp_f32_e32 v156, v156
	v_rcp_f32_e32 v157, v157
	v_rcp_f32_e32 v158, v158
	v_rcp_f32_e32 v159, v159
	v_mul_f32_e32 v156, v74, v156
	v_mul_f32_e32 v157, v75, v157
	v_mul_f32_e32 v158, v76, v158
	v_mul_f32_e32 v159, v77, v159
	v_cvt_pk_bf16_f32 v146, v156, v157
	v_cvt_pk_bf16_f32 v147, v158, v159
	s_nop 1
	v_permlane16_swap_b32 v144, v146
	v_permlane16_swap_b32 v145, v147
	global_store_dwordx4 v133, v[144:147], s[92:93] offset:128
	v_mul_f32_e32 v152, 0xbfb8aa3b, v70
	v_mul_f32_e32 v153, 0xbfb8aa3b, v71
	v_mul_f32_e32 v154, 0xbfb8aa3b, v72
	v_mul_f32_e32 v155, 0xbfb8aa3b, v73
	v_exp_f32_e32 v152, v152
	v_exp_f32_e32 v153, v153
	v_exp_f32_e32 v154, v154
	v_exp_f32_e32 v155, v155
	v_add_f32_e32 v152, 1.0, v152
	v_add_f32_e32 v153, 1.0, v153
	v_add_f32_e32 v154, 1.0, v154
	v_add_f32_e32 v155, 1.0, v155
	v_rcp_f32_e32 v152, v152
	v_rcp_f32_e32 v153, v153
	v_rcp_f32_e32 v154, v154
; DI unsigned pk2(float lo, float hi) { const f32x2 v = {lo, hi}; const bf16x2_t b = __builtin_convertvector(v, bf16x2_t); return __builtin_bit_cast(unsigned, b); }
; DI float sigmoid_f(float x) { return __builtin_amdgcn_rcpf(1.f + __builtin_amdgcn_exp2f(x * -1.44269504089f)); }
; DI float silu_f(float x) { return x * sigmoid_f(x); }
; DI void unit_B1(const Params& p, char* lds, int l, int chunk) {
;     ...
;         for (int nt = 0; nt < 8; ++nt) {
;             f32x4 v = acc[mt][nt];
;             if (wc >= 2) {
;                 v[0] = silu_f(v[0]); v[1] = silu_f(v[1]); v[2] = silu_f(v[2]); v[3] = silu_f(v[3]);
;                 const int col = (wc & 1) * 128 + nt * 16 + quad * 4;
;                 *(u32x2*)(sgd + (size_t)tok * 256 + col) = (u32x2){pk2(v[0], v[1]), pk2(v[2], v[3])};
	v_rcp_f32_e32 v155, v155
	v_mul_f32_e32 v152, v70, v152
	v_mul_f32_e32 v153, v71, v153
	v_mul_f32_e32 v154, v72, v154
	v_mul_f32_e32 v155, v73, v155
	v_cvt_pk_bf16_f32 v148, v152, v153
	v_cvt_pk_bf16_f32 v149, v154, v155
	v_mul_f32_e32 v156, 0xbfb8aa3b, v66
	v_mul_f32_e32 v157, 0xbfb8aa3b, v67
	v_mul_f32_e32 v158, 0xbfb8aa3b, v68
	v_mul_f32_e32 v159, 0xbfb8aa3b, v69
	v_exp_f32_e32 v156, v156
	v_exp_f32_e32 v157, v157
	v_exp_f32_e32 v158, v158
	v_exp_f32_e32 v159, v159
	v_add_f32_e32 v156, 1.0, v156
	v_add_f32_e32 v157, 1.0, v157
	v_add_f32_e32 v158, 1.0, v158
	v_add_f32_e32 v159, 1.0, v159
	v_rcp_f32_e32 v156, v156
	v_rcp_f32_e32 v157, v157
	v_rcp_f32_e32 v158, v158
	v_rcp_f32_e32 v159, v159
	v_mul_f32_e32 v156, v66, v156
	v_mul_f32_e32 v157, v67, v157
	v_mul_f32_e32 v158, v68, v158
	v_mul_f32_e32 v159, v69, v159
	v_cvt_pk_bf16_f32 v150, v156, v157
	v_cvt_pk_bf16_f32 v151, v158, v159
	s_nop 1
	v_permlane16_swap_b32 v148, v150
	v_permlane16_swap_b32 v149, v151
	global_store_dwordx4 v133, v[148:151], s[92:93] offset:192
	s_add_u32 s92, s92, 0x2000
	s_addc_u32 s93, s93, 0
	v_mul_f32_e32 v152, 0xbfb8aa3b, v62
	v_mul_f32_e32 v153, 0xbfb8aa3b, v63
	v_mul_f32_e32 v154, 0xbfb8aa3b, v64
	v_mul_f32_e32 v155, 0xbfb8aa3b, v65
	v_exp_f32_e32 v152, v152
	v_exp_f32_e32 v153, v153
	v_exp_f32_e32 v154, v154
	v_exp_f32_e32 v155, v155
	v_add_f32_e32 v152, 1.0, v152
	v_add_f32_e32 v153, 1.0, v153
	v_add_f32_e32 v154, 1.0, v154
	v_add_f32_e32 v155, 1.0, v155
	v_rcp_f32_e32 v152, v152
	v_rcp_f32_e32 v153, v153
	v_rcp_f32_e32 v154, v154
	v_rcp_f32_e32 v155, v155
	v_mul_f32_e32 v152, v62, v152
	v_mul_f32_e32 v153, v63, v153
	v_mul_f32_e32 v154, v64, v154
	v_mul_f32_e32 v155, v65, v155
	v_cvt_pk_bf16_f32 v136, v152, v153
	v_cvt_pk_bf16_f32 v137, v154, v155
	v_mul_f32_e32 v156, 0xbfb8aa3b, v58
	v_mul_f32_e32 v157, 0xbfb8aa3b, v59
	v_mul_f32_e32 v158, 0xbfb8aa3b, v60
	v_mul_f32_e32 v159, 0xbfb8aa3b, v61
	v_exp_f32_e32 v156, v156
	v_exp_f32_e32 v157, v157
	v_exp_f32_e32 v158, v158
	v_exp_f32_e32 v159, v159
	v_add_f32_e32 v156, 1.0, v156
	v_add_f32_e32 v157, 1.0, v157
	v_add_f32_e32 v158, 1.0, v158
	v_add_f32_e32 v159, 1.0, v159
	v_rcp_f32_e32 v156, v156
	v_rcp_f32_e32 v157, v157
	v_rcp_f32_e32 v158, v158
	v_rcp_f32_e32 v159, v159
	v_mul_f32_e32 v156, v58, v156
	v_mul_f32_e32 v157, v59, v157
	v_mul_f32_e32 v158, v60, v158
	v_mul_f32_e32 v159, v61, v159
	v_cvt_pk_bf16_f32 v138, v156, v157
	v_cvt_pk_bf16_f32 v139, v158, v159
	s_nop 1
	v_permlane16_swap_b32 v136, v138
	v_permlane16_swap_b32 v137, v139
	global_store_dwordx4 v133, v[136:139], s[92:93]
	v_mul_f32_e32 v152, 0xbfb8aa3b, v54
	v_mul_f32_e32 v153, 0xbfb8aa3b, v55
	v_mul_f32_e32 v154, 0xbfb8aa3b, v56
	v_mul_f32_e32 v155, 0xbfb8aa3b, v57
	v_exp_f32_e32 v152, v152
	v_exp_f32_e32 v153, v153
	v_exp_f32_e32 v154, v154
	v_exp_f32_e32 v155, v155
	v_add_f32_e32 v152, 1.0, v152
	v_add_f32_e32 v153, 1.0, v153
	v_add_f32_e32 v154, 1.0, v154
	v_add_f32_e32 v155, 1.0, v155
	v_rcp_f32_e32 v152, v152
	v_rcp_f32_e32 v153, v153
	v_rcp_f32_e32 v154, v154
	v_rcp_f32_e32 v155, v155
	v_mul_f32_e32 v152, v54, v152
	v_mul_f32_e32 v153, v55, v153
	v_mul_f32_e32 v154, v56, v154
	v_mul_f32_e32 v155, v57, v155
	v_cvt_pk_bf16_f32 v140, v152, v153
	v_cvt_pk_bf16_f32 v141, v154, v155
	v_mul_f32_e32 v156, 0xbfb8aa3b, v50
	v_mul_f32_e32 v157, 0xbfb8aa3b, v51
	v_mul_f32_e32 v158, 0xbfb8aa3b, v52
	v_mul_f32_e32 v159, 0xbfb8aa3b, v53
	v_exp_f32_e32 v156, v156
	v_exp_f32_e32 v157, v157
	v_exp_f32_e32 v158, v158
	v_exp_f32_e32 v159, v159
	v_add_f32_e32 v156, 1.0, v156
	v_add_f32_e32 v157, 1.0, v157
	v_add_f32_e32 v158, 1.0, v158
	v_add_f32_e32 v159, 1.0, v159
	v_rcp_f32_e32 v156, v156
	v_rcp_f32_e32 v157, v157
	v_rcp_f32_e32 v158, v158
	v_rcp_f32_e32 v159, v159
	v_mul_f32_e32 v156, v50, v156
	v_mul_f32_e32 v157, v51, v157
	v_mul_f32_e32 v158, v52, v158
	v_mul_f32_e32 v159, v53, v159
	v_cvt_pk_bf16_f32 v142, v156, v157
	v_cvt_pk_bf16_f32 v143, v158, v159
	s_nop 1
	v_permlane16_swap_b32 v140, v142
	v_permlane16_swap_b32 v141, v143
	global_store_dwordx4 v133, v[140:143], s[92:93] offset:64
	v_mul_f32_e32 v152, 0xbfb8aa3b, v46
	v_mul_f32_e32 v153, 0xbfb8aa3b, v47
	v_mul_f32_e32 v154, 0xbfb8aa3b, v48
	v_mul_f32_e32 v155, 0xbfb8aa3b, v49
	v_exp_f32_e32 v152, v152
	v_exp_f32_e32 v153, v153
	v_exp_f32_e32 v154, v154
	v_exp_f32_e32 v155, v155
	v_add_f32_e32 v152, 1.0, v152
	v_add_f32_e32 v153, 1.0, v153
	v_add_f32_e32 v154, 1.0, v154
	v_add_f32_e32 v155, 1.0, v155
	v_rcp_f32_e32 v152, v152
	v_rcp_f32_e32 v153, v153
	v_rcp_f32_e32 v154, v154
	v_rcp_f32_e32 v155, v155
	v_mul_f32_e32 v152, v46, v152
	v_mul_f32_e32 v153, v47, v153
	v_mul_f32_e32 v154, v48, v154
	v_mul_f32_e32 v155, v49, v155
	v_cvt_pk_bf16_f32 v144, v152, v153
	v_cvt_pk_bf16_f32 v145, v154, v155
	v_mul_f32_e32 v156, 0xbfb8aa3b, v42
	v_mul_f32_e32 v157, 0xbfb8aa3b, v43
	v_mul_f32_e32 v158, 0xbfb8aa3b, v44
	v_mul_f32_e32 v159, 0xbfb8aa3b, v45
	v_exp_f32_e32 v156, v156
	v_exp_f32_e32 v157, v157
	v_exp_f32_e32 v158, v158
	v_exp_f32_e32 v159, v159
	v_add_f32_e32 v156, 1.0, v156
	v_add_f32_e32 v157, 1.0, v157
	v_add_f32_e32 v158, 1.0, v158
	v_add_f32_e32 v159, 1.0, v159
	v_rcp_f32_e32 v156, v156
	v_rcp_f32_e32 v157, v157
	v_rcp_f32_e32 v158, v158
	v_rcp_f32_e32 v159, v159
	v_mul_f32_e32 v156, v42, v156
	v_mul_f32_e32 v157, v43, v157
	v_mul_f32_e32 v158, v44, v158
	v_mul_f32_e32 v159, v45, v159
	v_cvt_pk_bf16_f32 v146, v156, v157
	v_cvt_pk_bf16_f32 v147, v158, v159
	s_nop 1
	v_permlane16_swap_b32 v144, v146
	v_permlane16_swap_b32 v145, v147
	global_store_dwordx4 v133, v[144:147], s[92:93] offset:128
	v_mul_f32_e32 v152, 0xbfb8aa3b, v38
	v_mul_f32_e32 v153, 0xbfb8aa3b, v39
	v_mul_f32_e32 v154, 0xbfb8aa3b, v40
; DI unsigned pk2(float lo, float hi) { const f32x2 v = {lo, hi}; const bf16x2_t b = __builtin_convertvector(v, bf16x2_t); return __builtin_bit_cast(unsigned, b); }
; DI float sigmoid_f(float x) { return __builtin_amdgcn_rcpf(1.f + __builtin_amdgcn_exp2f(x * -1.44269504089f)); }
; DI float silu_f(float x) { return x * sigmoid_f(x); }
; DI void unit_B1(const Params& p, char* lds, int l, int chunk) {
;     ...
;         for (int nt = 0; nt < 8; ++nt) {
;             f32x4 v = acc[mt][nt];
;             if (wc >= 2) {
;                 v[0] = silu_f(v[0]); v[1] = silu_f(v[1]); v[2] = silu_f(v[2]); v[3] = silu_f(v[3]);
;                 const int col = (wc & 1) * 128 + nt * 16 + quad * 4;
;                 *(u32x2*)(sgd + (size_t)tok * 256 + col) = (u32x2){pk2(v[0], v[1]), pk2(v[2], v[3])};
	v_mul_f32_e32 v155, 0xbfb8aa3b, v41
	v_exp_f32_e32 v152, v152
	v_exp_f32_e32 v153, v153
	v_exp_f32_e32 v154, v154
	v_exp_f32_e32 v155, v155
	v_add_f32_e32 v152, 1.0, v152
	v_add_f32_e32 v153, 1.0, v153
	v_add_f32_e32 v154, 1.0, v154
	v_add_f32_e32 v155, 1.0, v155
	v_rcp_f32_e32 v152, v152
	v_rcp_f32_e32 v153, v153
	v_rcp_f32_e32 v154, v154
	v_rcp_f32_e32 v155, v155
	v_mul_f32_e32 v152, v38, v152
	v_mul_f32_e32 v153, v39, v153
	v_mul_f32_e32 v154, v40, v154
	v_mul_f32_e32 v155, v41, v155
	v_cvt_pk_bf16_f32 v148, v152, v153
	v_cvt_pk_bf16_f32 v149, v154, v155
	v_mul_f32_e32 v156, 0xbfb8aa3b, v34
	v_mul_f32_e32 v157, 0xbfb8aa3b, v35
	v_mul_f32_e32 v158, 0xbfb8aa3b, v36
	v_mul_f32_e32 v159, 0xbfb8aa3b, v37
	v_exp_f32_e32 v156, v156
	v_exp_f32_e32 v157, v157
	v_exp_f32_e32 v158, v158
	v_exp_f32_e32 v159, v159
	v_add_f32_e32 v156, 1.0, v156
	v_add_f32_e32 v157, 1.0, v157
	v_add_f32_e32 v158, 1.0, v158
	v_add_f32_e32 v159, 1.0, v159
	v_rcp_f32_e32 v156, v156
	v_rcp_f32_e32 v157, v157
	v_rcp_f32_e32 v158, v158
	v_rcp_f32_e32 v159, v159
	v_mul_f32_e32 v156, v34, v156
	v_mul_f32_e32 v157, v35, v157
	v_mul_f32_e32 v158, v36, v158
	v_mul_f32_e32 v159, v37, v159
	v_cvt_pk_bf16_f32 v150, v156, v157
	v_cvt_pk_bf16_f32 v151, v158, v159
	s_nop 1
	v_permlane16_swap_b32 v148, v150
	v_permlane16_swap_b32 v149, v151
	global_store_dwordx4 v133, v[148:151], s[92:93] offset:192
	s_add_u32 s92, s92, 0x2000
	s_addc_u32 s93, s93, 0
	v_mul_f32_e32 v152, 0xbfb8aa3b, v30
	v_mul_f32_e32 v153, 0xbfb8aa3b, v31
	v_mul_f32_e32 v154, 0xbfb8aa3b, v32
	v_mul_f32_e32 v155, 0xbfb8aa3b, v33
	v_exp_f32_e32 v152, v152
	v_exp_f32_e32 v153, v153
	v_exp_f32_e32 v154, v154
	v_exp_f32_e32 v155, v155
	v_add_f32_e32 v152, 1.0, v152
	v_add_f32_e32 v153, 1.0, v153
	v_add_f32_e32 v154, 1.0, v154
	v_add_f32_e32 v155, 1.0, v155
	v_rcp_f32_e32 v152, v152
	v_rcp_f32_e32 v153, v153
	v_rcp_f32_e32 v154, v154
	v_rcp_f32_e32 v155, v155
	v_mul_f32_e32 v152, v30, v152
	v_mul_f32_e32 v153, v31, v153
	v_mul_f32_e32 v154, v32, v154
	v_mul_f32_e32 v155, v33, v155
	v_cvt_pk_bf16_f32 v136, v152, v153
	v_cvt_pk_bf16_f32 v137, v154, v155
	v_mul_f32_e32 v156, 0xbfb8aa3b, v26
	v_mul_f32_e32 v157, 0xbfb8aa3b, v27
	v_mul_f32_e32 v158, 0xbfb8aa3b, v28
	v_mul_f32_e32 v159, 0xbfb8aa3b, v29
	v_exp_f32_e32 v156, v156
	v_exp_f32_e32 v157, v157
	v_exp_f32_e32 v158, v158
	v_exp_f32_e32 v159, v159
	v_add_f32_e32 v156, 1.0, v156
	v_add_f32_e32 v157, 1.0, v157
	v_add_f32_e32 v158, 1.0, v158
	v_add_f32_e32 v159, 1.0, v159
	v_rcp_f32_e32 v156, v156
	v_rcp_f32_e32 v157, v157
	v_rcp_f32_e32 v158, v158
	v_rcp_f32_e32 v159, v159
	v_mul_f32_e32 v156, v26, v156
	v_mul_f32_e32 v157, v27, v157
	v_mul_f32_e32 v158, v28, v158
	v_mul_f32_e32 v159, v29, v159
	v_cvt_pk_bf16_f32 v138, v156, v157
	v_cvt_pk_bf16_f32 v139, v158, v159
	s_nop 1
	v_permlane16_swap_b32 v136, v138
	v_permlane16_swap_b32 v137, v139
	global_store_dwordx4 v133, v[136:139], s[92:93]
	v_mul_f32_e32 v152, 0xbfb8aa3b, v22
	v_mul_f32_e32 v153, 0xbfb8aa3b, v23
	v_mul_f32_e32 v154, 0xbfb8aa3b, v24
	v_mul_f32_e32 v155, 0xbfb8aa3b, v25
	v_exp_f32_e32 v152, v152
	v_exp_f32_e32 v153, v153
	v_exp_f32_e32 v154, v154
	v_exp_f32_e32 v155, v155
	v_add_f32_e32 v152, 1.0, v152
	v_add_f32_e32 v153, 1.0, v153
	v_add_f32_e32 v154, 1.0, v154
	v_add_f32_e32 v155, 1.0, v155
	v_rcp_f32_e32 v152, v152
	v_rcp_f32_e32 v153, v153
	v_rcp_f32_e32 v154, v154
	v_rcp_f32_e32 v155, v155
	v_mul_f32_e32 v152, v22, v152
	v_mul_f32_e32 v153, v23, v153
	v_mul_f32_e32 v154, v24, v154
	v_mul_f32_e32 v155, v25, v155
	v_cvt_pk_bf16_f32 v140, v152, v153
	v_cvt_pk_bf16_f32 v141, v154, v155
	v_mul_f32_e32 v156, 0xbfb8aa3b, v18
	v_mul_f32_e32 v157, 0xbfb8aa3b, v19
	v_mul_f32_e32 v158, 0xbfb8aa3b, v20
	v_mul_f32_e32 v159, 0xbfb8aa3b, v21
	v_exp_f32_e32 v156, v156
	v_exp_f32_e32 v157, v157
	v_exp_f32_e32 v158, v158
	v_exp_f32_e32 v159, v159
	v_add_f32_e32 v156, 1.0, v156
	v_add_f32_e32 v157, 1.0, v157
	v_add_f32_e32 v158, 1.0, v158
	v_add_f32_e32 v159, 1.0, v159
	v_rcp_f32_e32 v156, v156
	v_rcp_f32_e32 v157, v157
	v_rcp_f32_e32 v158, v158
; DI unsigned pk2(float lo, float hi) { const f32x2 v = {lo, hi}; const bf16x2_t b = __builtin_convertvector(v, bf16x2_t); return __builtin_bit_cast(unsigned, b); }
; DI float silu_f(float x) { return x * sigmoid_f(x); }
; DI void unit_B1(const Params& p, char* lds, int l, int chunk) {
;     ...
;         for (int nt = 0; nt < 8; ++nt) {
;             f32x4 v = acc[mt][nt];
;             if (wc >= 2) {
;                 v[0] = silu_f(v[0]); v[1] = silu_f(v[1]); v[2] = silu_f(v[2]); v[3] = silu_f(v[3]);
;                 const int col = (wc & 1) * 128 + nt * 16 + quad * 4;
;                 *(u32x2*)(sgd + (size_t)tok * 256 + col) = (u32x2){pk2(v[0], v[1]), pk2(v[2], v[3])};
;             } else {
;                 const int g = (wc & 1) * 8 + nt, tb = (chunk & 15) * 128 + tok;
;                 *(u32x2*)(xbd + ((size_t)g * 2048 + tb) * 16 + quad * 4) = (u32x2){pk2(v[0], v[1]), pk2(v[2], v[3])};
;             }
;         }
;     }
	v_rcp_f32_e32 v159, v159
	v_mul_f32_e32 v156, v18, v156
	v_mul_f32_e32 v157, v19, v157
	v_mul_f32_e32 v158, v20, v158
	v_mul_f32_e32 v159, v21, v159
	v_cvt_pk_bf16_f32 v142, v156, v157
	v_cvt_pk_bf16_f32 v143, v158, v159
	s_nop 1
	v_permlane16_swap_b32 v140, v142
	v_permlane16_swap_b32 v141, v143
	global_store_dwordx4 v133, v[140:143], s[92:93] offset:64
	v_mul_f32_e32 v152, 0xbfb8aa3b, v14
	v_mul_f32_e32 v153, 0xbfb8aa3b, v15
	v_mul_f32_e32 v154, 0xbfb8aa3b, v16
	v_mul_f32_e32 v155, 0xbfb8aa3b, v17
	v_exp_f32_e32 v152, v152
	v_exp_f32_e32 v153, v153
	v_exp_f32_e32 v154, v154
	v_exp_f32_e32 v155, v155
	v_add_f32_e32 v152, 1.0, v152
	v_add_f32_e32 v153, 1.0, v153
	v_add_f32_e32 v154, 1.0, v154
	v_add_f32_e32 v155, 1.0, v155
	v_rcp_f32_e32 v152, v152
	v_rcp_f32_e32 v153, v153
	v_rcp_f32_e32 v154, v154
	v_rcp_f32_e32 v155, v155
	v_mul_f32_e32 v152, v14, v152
	v_mul_f32_e32 v153, v15, v153
	v_mul_f32_e32 v154, v16, v154
	v_mul_f32_e32 v155, v17, v155
	v_cvt_pk_bf16_f32 v144, v152, v153
	v_cvt_pk_bf16_f32 v145, v154, v155
	v_mul_f32_e32 v156, 0xbfb8aa3b, v10
	v_mul_f32_e32 v157, 0xbfb8aa3b, v11
	v_mul_f32_e32 v158, 0xbfb8aa3b, v12
	v_mul_f32_e32 v159, 0xbfb8aa3b, v13
	v_exp_f32_e32 v156, v156
	v_exp_f32_e32 v157, v157
	v_exp_f32_e32 v158, v158
	v_exp_f32_e32 v159, v159
	v_add_f32_e32 v156, 1.0, v156
	v_add_f32_e32 v157, 1.0, v157
	v_add_f32_e32 v158, 1.0, v158
	v_add_f32_e32 v159, 1.0, v159
	v_rcp_f32_e32 v156, v156
	v_rcp_f32_e32 v157, v157
	v_rcp_f32_e32 v158, v158
	v_rcp_f32_e32 v159, v159
	v_mul_f32_e32 v156, v10, v156
	v_mul_f32_e32 v157, v11, v157
	v_mul_f32_e32 v158, v12, v158
	v_mul_f32_e32 v159, v13, v159
	v_cvt_pk_bf16_f32 v146, v156, v157
	v_cvt_pk_bf16_f32 v147, v158, v159
	s_nop 1
	v_permlane16_swap_b32 v144, v146
	v_permlane16_swap_b32 v145, v147
	global_store_dwordx4 v133, v[144:147], s[92:93] offset:128
	v_mul_f32_e32 v152, 0xbfb8aa3b, v6
	v_mul_f32_e32 v153, 0xbfb8aa3b, v7
	v_mul_f32_e32 v154, 0xbfb8aa3b, v8
	v_mul_f32_e32 v155, 0xbfb8aa3b, v9
	v_exp_f32_e32 v152, v152
	v_exp_f32_e32 v153, v153
	v_exp_f32_e32 v154, v154
	v_exp_f32_e32 v155, v155
	v_add_f32_e32 v152, 1.0, v152
	v_add_f32_e32 v153, 1.0, v153
	v_add_f32_e32 v154, 1.0, v154
	v_add_f32_e32 v155, 1.0, v155
	v_rcp_f32_e32 v152, v152
	v_rcp_f32_e32 v153, v153
	v_rcp_f32_e32 v154, v154
	v_rcp_f32_e32 v155, v155
	v_mul_f32_e32 v152, v6, v152
	v_mul_f32_e32 v153, v7, v153
	v_mul_f32_e32 v154, v8, v154
	v_mul_f32_e32 v155, v9, v155
	v_cvt_pk_bf16_f32 v148, v152, v153
	v_cvt_pk_bf16_f32 v149, v154, v155
	v_mul_f32_e32 v156, 0xbfb8aa3b, v2
	v_mul_f32_e32 v157, 0xbfb8aa3b, v3
	v_mul_f32_e32 v158, 0xbfb8aa3b, v4
	v_mul_f32_e32 v159, 0xbfb8aa3b, v5
	v_exp_f32_e32 v156, v156
	v_exp_f32_e32 v157, v157
	v_exp_f32_e32 v158, v158
	v_exp_f32_e32 v159, v159
	v_add_f32_e32 v156, 1.0, v156
	v_add_f32_e32 v157, 1.0, v157
	v_add_f32_e32 v158, 1.0, v158
	v_add_f32_e32 v159, 1.0, v159
	v_rcp_f32_e32 v156, v156
	v_rcp_f32_e32 v157, v157
	v_rcp_f32_e32 v158, v158
	v_rcp_f32_e32 v159, v159
	v_mul_f32_e32 v156, v2, v156
	v_mul_f32_e32 v157, v3, v157
	v_mul_f32_e32 v158, v4, v158
	v_mul_f32_e32 v159, v5, v159
	v_cvt_pk_bf16_f32 v150, v156, v157
	v_cvt_pk_bf16_f32 v151, v158, v159
	s_nop 1
	v_permlane16_swap_b32 v148, v150
	v_permlane16_swap_b32 v149, v151
	global_store_dwordx4 v133, v[148:151], s[92:93] offset:192
.LBB0_897:
.LBB0_899:
.LBB0_901:
.LBB0_903:
.LBB0_905:
.LBB0_907:
.LBB0_909:
.LBB0_911:
.LBB0_913:
.LBB0_915:
.LBB0_917:
.LBB0_919:
.LBB0_921:
.LBB0_923:
.LBB0_925:
.LBB0_927:
.LBB0_929:
.LBB0_931:
.LBB0_932:
.LBB0_933:
.LBB0_934:
.LBB0_935:
.LBB0_936:
.LBB0_937:
.LBB0_938:
.LBB0_939:
.LBB0_940:
.LBB0_941:
.LBB0_942:
.LBB0_943:
.LBB0_944:
.LBB0_945:
.LBB0_947:
.LBB0_949:
.LBB0_950:
.LBB0_951:
.LBB0_952:
.LBB0_953:
.LBB0_954:
.LBB0_955:
.LBB0_956:
.LBB0_957:
.LBB0_958:
.LBB0_959:
.LBB0_960:
.LBB0_961:
.LBB0_962:
.LBB0_963:
.LBB0_965:
.LBB0_967:
.LBB0_968:
.LBB0_969:
.LBB0_970:
.LBB0_971:
.LBB0_972:
.LBB0_973:
.LBB0_974:
.LBB0_975:
.LBB0_976:
.LBB0_977:
.LBB0_978:
.LBB0_979:
.LBB0_980:
.Lb1e_done:
	s_mov_b64 s[8:9], -1

; template <int N> DI void wait_vm() { asm volatile("s_waitcnt vmcnt(%0)" ::"n"(N) : "memory"); }
; DI void signal_done(unsigned* c) {
;     wait_vm<0>();
;     __syncthreads();
;     if (threadIdx.x == 0) { __builtin_amdgcn_fence(__ATOMIC_RELEASE, "agent"); __hip_atomic_fetch_add(c, 1u, __ATOMIC_RELAXED, __HIP_MEMORY_SCOPE_AGENT); }
; }
; DI void unit_B1(const Params& p, char* lds, int l, int chunk) {
;     ...
;     signal_done(WS_PTR(unsigned, OFF_HL) + 128 + l * 16 + (chunk >> 4));
.Lcen_b1_done:
	v_readlane_b32 s1, v243, 38
	s_nop 3
	s_lshr_b32 s1, s1, 1
	s_add_u32 s1, s1, 1
	v_add_u32_e32 v23, 0x180, v2
	v_mov_b32_e32 v24, 0x348
	global_atomic_add v0, v23, v3, s[10:11] sc0
	s_waitcnt vmcnt(0)
	v_readfirstlane_b32 s6, v0
	s_nop 3
	s_add_u32 s6, s6, 1
	s_mul_i32 s7, s1, s3
	s_cmp_eq_u32 s6, s7
	s_cbranch_scc0 .LBB0_661
	global_atomic_add v24, v3, s[10:11]
	s_branch .LBB0_661
